# nt cache policy also on once-read f32 weight loads (conversion sites + w_ada), on top of scan nt
# speedup vs baseline: 1.0148x; 1.0015x over previous
; __device__ __forceinline__ void p0_item_load(const float* W, int N, int item, int lane, f32x4 (&wv)[8]) {
;     const int nblk = N / 32, kb = item / nblk, nb = item % nblk, k0 = 64 * kb, n0 = 32 * nb;
; #pragma unroll
;     for (int i = 0; i < 8; ++i) wv[i] = *(const f32x4*)(W + (size_t)(k0 + 8 * i + (lane >> 3)) * N + n0 + 4 * (lane & 7));
; }
; __device__ __forceinline__ void cv_load(const Args& a, int l, int it, int lane, f32x4 (&wv)[8]) {
;     ...
;     else if (it < CV_B) p0_item_load(a.in[I_WOUT] + (size_t)l * DM * DM, DM, it - CV_A, lane, wv);
;     else if (it < CV_C) p0_item_load(a.in[I_W1] + (size_t)l * DM * DFF, DFF, it - CV_B, lane, wv);
;     else p0_item_load(a.in[I_W2] + (size_t)l * DFF * DM, DM, it - CV_C, lane, wv);
; }
.LBB0_19:
	s_cmpk_gt_i32 s49, 0x161f
	s_cselect_b64 s[12:13], -1, 0
	s_mov_b64 s[82:83], -1
	s_and_b64 vcc, exec, s[12:13]
	s_cbranch_vccz .LBB0_29
	s_cmpk_gt_u32 s49, 0x1e1f
	s_cbranch_scc0 .LBB0_26
	s_lshl_b64 s[82:83], s[80:81], 26
	s_cmpk_gt_u32 s49, 0x3e1f
	s_mov_b64 s[84:85], -1
	s_cbranch_scc0 .LBB0_23
	s_add_u32 s50, s8, s82
	s_addc_u32 s53, s9, s83
	s_add_i32 s52, s49, 0xffffc1e0
	s_and_b32 s54, s52, 0xffffffc0
	s_lshl_b32 s52, s52, 7
	s_and_b32 s52, s52, 0x1f80
	s_waitcnt vmcnt(6)
	v_add_u32_e32 v32, s54, v69
	s_add_u32 s52, s50, s52
	s_addc_u32 s53, s53, 0
	v_ashrrev_i32_e32 v33, 31, v32
	v_lshl_add_u64 v[34:35], s[52:53], 0, v[64:65]
	v_lshlrev_b64 v[32:33], 13, v[32:33]
	s_waitcnt vmcnt(0)
	v_lshl_add_u64 v[60:61], v[34:35], 0, v[32:33]
	v_add_co_u32_e32 v32, vcc, s40, v60
	s_mov_b64 s[84:85], 0
	s_nop 0
	v_addc_co_u32_e32 v33, vcc, 0, v61, vcc
	v_add_co_u32_e32 v40, vcc, s41, v60
	global_load_dwordx4 v[36:39], v[60:61], off nt
	s_nop 0
	global_load_dwordx4 v[32:35], v[32:33], off nt
	v_addc_co_u32_e32 v41, vcc, 0, v61, vcc
	v_add_co_u32_e32 v42, vcc, s42, v60
	s_nop 1
	v_addc_co_u32_e32 v43, vcc, 0, v61, vcc
	v_add_co_u32_e32 v48, vcc, s43, v60
	global_load_dwordx4 v[44:47], v[40:41], off nt
	s_nop 0
	global_load_dwordx4 v[40:43], v[42:43], off nt
	v_addc_co_u32_e32 v49, vcc, 0, v61, vcc
	v_add_co_u32_e32 v50, vcc, s44, v60
	s_nop 1
	v_addc_co_u32_e32 v51, vcc, 0, v61, vcc
	v_add_co_u32_e32 v52, vcc, s45, v60
	global_load_dwordx4 v[56:59], v[48:49], off nt
	s_nop 0
	global_load_dwordx4 v[48:51], v[50:51], off nt
	v_addc_co_u32_e32 v53, vcc, 0, v61, vcc
	global_load_dwordx4 v[52:55], v[52:53], off nt
	v_lshl_add_u64 v[60:61], v[60:61], 0, s[72:73]
.LBB0_23:
	s_andn2_b64 vcc, exec, s[84:85]
	s_cbranch_vccnz .LBB0_25
	s_add_u32 s50, s6, s82
	s_addc_u32 s53, s7, s83
	s_add_i32 s52, s49, 0xffffe1e0
	s_bfe_u32 s54, s52, 0x80008
	s_lshl_b32 s52, s52, 7
	s_and_b32 s52, s52, 0x7f80
	s_waitcnt vmcnt(5)
	v_lshl_add_u32 v32, s54, 6, v69
	s_add_u32 s52, s50, s52
	s_addc_u32 s53, s53, 0
	v_ashrrev_i32_e32 v33, 31, v32
	v_lshl_add_u64 v[34:35], s[52:53], 0, v[64:65]
	v_lshlrev_b64 v[32:33], 15, v[32:33]
	s_waitcnt vmcnt(0)
	v_lshl_add_u64 v[60:61], v[34:35], 0, v[32:33]
	v_add_co_u32_e32 v32, vcc, s43, v60
	s_mov_b32 s50, 0x80000
	s_nop 0
	v_addc_co_u32_e32 v33, vcc, 0, v61, vcc
	s_waitcnt vmcnt(3)
	v_add_co_u32_e32 v40, vcc, s50, v60
	s_mov_b32 s50, 0xc0000
	s_nop 0
	v_addc_co_u32_e32 v41, vcc, 0, v61, vcc
	v_add_co_u32_e32 v42, vcc, s50, v60
	s_mov_b32 s50, 0x100000
	s_nop 0
	v_addc_co_u32_e32 v43, vcc, 0, v61, vcc
	s_waitcnt vmcnt(1)
	v_add_co_u32_e32 v48, vcc, s50, v60
	s_mov_b32 s50, 0x140000
	s_nop 0
	v_addc_co_u32_e32 v49, vcc, 0, v61, vcc
	v_add_co_u32_e32 v50, vcc, s50, v60
	s_mov_b32 s50, 0x180000
	s_nop 0
	v_addc_co_u32_e32 v51, vcc, 0, v61, vcc
	s_waitcnt vmcnt(0)
	v_add_co_u32_e32 v52, vcc, s50, v60
	global_load_dwordx4 v[36:39], v[60:61], off nt
	s_nop 0
	global_load_dwordx4 v[32:35], v[32:33], off nt
	v_addc_co_u32_e32 v53, vcc, 0, v61, vcc
	global_load_dwordx4 v[44:47], v[40:41], off nt
	s_nop 0
	global_load_dwordx4 v[40:43], v[42:43], off nt
	s_nop 0
	global_load_dwordx4 v[56:59], v[48:49], off nt
	s_nop 0
	global_load_dwordx4 v[48:51], v[50:51], off nt
	v_lshl_add_u64 v[60:61], v[60:61], 0, s[74:75]
	global_load_dwordx4 v[52:55], v[52:53], off nt

; __device__ __forceinline__ void p0_item_load(const float* W, int N, int item, int lane, f32x4 (&wv)[8]) {
;     const int nblk = N / 32, kb = item / nblk, nb = item % nblk, k0 = 64 * kb, n0 = 32 * nb;
; #pragma unroll
;     for (int i = 0; i < 8; ++i) wv[i] = *(const f32x4*)(W + (size_t)(k0 + 8 * i + (lane >> 3)) * N + n0 + 4 * (lane & 7));
; }
; __device__ __forceinline__ void cv_load(const Args& a, int l, int it, int lane, f32x4 (&wv)[8]) {
;     ...
;     else if (it < CV_B) p0_item_load(a.in[I_WOUT] + (size_t)l * DM * DM, DM, it - CV_A, lane, wv);
;     else if (it < CV_C) p0_item_load(a.in[I_W1] + (size_t)l * DM * DFF, DFF, it - CV_B, lane, wv);
;     else p0_item_load(a.in[I_W2] + (size_t)l * DFF * DM, DM, it - CV_C, lane, wv);
; }
.LBB0_26:
	s_andn2_b64 vcc, exec, s[82:83]
	s_cbranch_vccnz .LBB0_28
	s_lshl_b64 s[52:53], s[80:81], 24
	s_add_u32 s50, s4, s52
	s_addc_u32 s53, s5, s53
	s_add_i32 s52, s49, 0xffffe9e0
	s_and_b32 s54, s52, 0xffc0
	s_lshl_b32 s52, s52, 7
	s_and_b32 s52, s52, 0x1f80
	s_waitcnt vmcnt(5)
	v_add_u32_e32 v32, s54, v69
	s_add_u32 s52, s50, s52
	s_addc_u32 s53, s53, 0
	v_ashrrev_i32_e32 v33, 31, v32
	v_lshl_add_u64 v[34:35], s[52:53], 0, v[64:65]
	v_lshlrev_b64 v[32:33], 13, v[32:33]
	s_waitcnt vmcnt(0)
	v_lshl_add_u64 v[60:61], v[34:35], 0, v[32:33]
	v_add_co_u32_e32 v32, vcc, s40, v60
	s_nop 1
	v_addc_co_u32_e32 v33, vcc, 0, v61, vcc
	s_waitcnt vmcnt(3)
	v_add_co_u32_e32 v40, vcc, s41, v60
	global_load_dwordx4 v[36:39], v[60:61], off nt
	s_nop 0
	global_load_dwordx4 v[32:35], v[32:33], off nt
	v_addc_co_u32_e32 v41, vcc, 0, v61, vcc
	v_add_co_u32_e32 v42, vcc, s42, v60
	s_nop 1
	v_addc_co_u32_e32 v43, vcc, 0, v61, vcc
	s_waitcnt vmcnt(3)
	v_add_co_u32_e32 v48, vcc, s43, v60
	global_load_dwordx4 v[44:47], v[40:41], off nt
	s_nop 0
	global_load_dwordx4 v[40:43], v[42:43], off nt
	v_addc_co_u32_e32 v49, vcc, 0, v61, vcc
	v_add_co_u32_e32 v50, vcc, s44, v60
	s_nop 1
	v_addc_co_u32_e32 v51, vcc, 0, v61, vcc
	s_waitcnt vmcnt(4)
	v_add_co_u32_e32 v52, vcc, s45, v60
	global_load_dwordx4 v[56:59], v[48:49], off nt
	s_nop 0
	global_load_dwordx4 v[48:51], v[50:51], off nt
	v_addc_co_u32_e32 v53, vcc, 0, v61, vcc
	global_load_dwordx4 v[52:55], v[52:53], off nt
	v_lshl_add_u64 v[60:61], v[60:61], 0, s[72:73]

; #define CV_MAP(g_, l_, it_) do { (l_) = lfix; \
;         if (MODE == 2) (it_) = CV_S0 + base + (g_); \
;         else if (MODE == 1) (it_) = cv_ritem(g_); \
;         else if ((g_) < CV_NR) (it_) = cv_ritem(g_); \
;         else { const int q_ = ((g_) - CV_NR) / CV_RPRO; (l_) = 1 + q_; (it_) = cv_ritem(CV_DEFER + ((g_) - CV_NR) - q_ * CV_RPRO); } } while (0)
; __device__ __forceinline__ void cv_load(const Args& a, int l, int it, int lane, f32x4 (&wv)[8]) {
;     ...
;     else if (it < CV_B) p0_item_load(a.in[I_WOUT] + (size_t)l * DM * DM, DM, it - CV_A, lane, wv);
;     else if (it < CV_C) p0_item_load(a.in[I_W1] + (size_t)l * DM * DFF, DFF, it - CV_B, lane, wv);
;     else p0_item_load(a.in[I_W2] + (size_t)l * DFF * DM, DM, it - CV_C, lane, wv);
; }
; template <int MODE>
; __device__ __forceinline__ void cv_jobs(const Frame& F, const Args& a, int lfix, int base, int njobs, int w, int nw) {
;     ...
;     for (int g = w; g < njobs; g += 2 * nw) {
;         const int g1 = g + nw; int l, it, l1, it1; CV_MAP(g, l, it); CV_MAP(g1, l1, it1);
;         cv_load(a, l, it, F.lane, sa);
;         if (g1 < njobs) cv_load(a, l1, it1, F.lane, sb);
;         cv_store(a, sa, scr, l, it, F.lane);
;         if (g1 < njobs) cv_store(a, sb, scr, l1, it1, F.lane);
;     }
.LBB0_29:
	s_andn2_b64 vcc, exec, s[82:83]
	s_mul_hi_i32 s50, s49, 0xb92143fb
	s_cbranch_vccnz .LBB0_31
	s_mul_i32 s52, s81, 0x2c40000
	s_mul_hi_u32 s53, s80, 0x2c40000
	s_add_i32 s53, s53, s52
	s_mul_i32 s52, s80, 0x2c40000
	s_add_u32 s54, s2, s52
	s_addc_u32 s55, s3, s53
	s_add_i32 s52, s50, s49
	s_lshr_b32 s53, s52, 31
	s_ashr_i32 s52, s52, 7
	s_add_i32 s53, s52, s53
	s_mul_i32 s52, s53, 0xb1
	s_sub_i32 s52, s49, s52
	s_lshl_b32 s52, s52, 5
	s_waitcnt vmcnt(0)
	v_lshl_add_u32 v62, s53, 6, v69
	s_ashr_i32 s53, s52, 31
	s_lshl_b64 s[52:53], s[52:53], 2
	s_add_u32 s52, s54, s52
	s_addc_u32 s53, s55, s53
	v_lshl_add_u64 v[60:61], s[52:53], 0, v[64:65]
	s_waitcnt vmcnt(5)
	v_add_u32_e32 v34, 8, v62
	s_waitcnt vmcnt(3)
	v_add_u32_e32 v40, 16, v62
	v_add_u32_e32 v42, 24, v62
	s_waitcnt vmcnt(1)
	v_add_u32_e32 v48, 32, v62
	v_add_u32_e32 v50, 40, v62
	s_waitcnt vmcnt(0)
	v_add_u32_e32 v52, 48, v62
	v_mad_i64_i32 v[32:33], s[52:53], v62, s46, v[60:61]
	v_mad_i64_i32 v[34:35], s[52:53], v34, s46, v[60:61]
	v_mad_i64_i32 v[40:41], s[52:53], v40, s46, v[60:61]
	v_mad_i64_i32 v[42:43], s[52:53], v42, s46, v[60:61]
	v_mad_i64_i32 v[48:49], s[52:53], v48, s46, v[60:61]
	v_mad_i64_i32 v[50:51], s[52:53], v50, s46, v[60:61]
	v_mad_i64_i32 v[52:53], s[52:53], v52, s46, v[60:61]
	global_load_dwordx4 v[36:39], v[32:33], off nt
	s_nop 0
	global_load_dwordx4 v[32:35], v[34:35], off nt
	s_nop 0
	global_load_dwordx4 v[44:47], v[40:41], off nt
	s_nop 0
	global_load_dwordx4 v[40:43], v[42:43], off nt
	s_nop 0
	global_load_dwordx4 v[56:59], v[48:49], off nt
	s_nop 0
	global_load_dwordx4 v[48:51], v[50:51], off nt
	v_add_u32_e32 v62, 56, v62
	global_load_dwordx4 v[52:55], v[52:53], off nt
	v_mad_i64_i32 v[60:61], s[52:53], v62, s46, v[60:61]
.LBB0_31:
	s_waitcnt vmcnt(0)
	global_load_dwordx4 v[60:63], v[60:61], off nt
	s_cmpk_lt_i32 s51, 0x6f80
	s_cselect_b64 s[82:83], -1, 0
	s_cmpk_gt_i32 s51, 0x6f7f
	s_cbranch_scc1 .LBB0_47
	s_cmpk_gt_i32 s48, 0x161f
	s_mov_b64 s[84:85], -1
	s_cbranch_scc0 .LBB0_42
	s_cmpk_gt_u32 s48, 0x1e1f
	s_cbranch_scc0 .LBB0_39
	s_lshl_b64 s[84:85], s[78:79], 26
	s_cmpk_gt_u32 s48, 0x3e1f
	s_mov_b64 s[86:87], -1
	s_cbranch_scc0 .LBB0_36
	s_add_u32 s51, s8, s84
	s_addc_u32 s53, s9, s85
	s_add_i32 s52, s48, 0xffffc1e0
	s_and_b32 s54, s52, 0xffffffc0
	s_lshl_b32 s52, s52, 7
	v_add_u32_e32 v2, s54, v69
	s_and_b32 s52, s52, 0x1f80
	s_add_u32 s52, s51, s52
	v_add_u32_e32 v10, 24, v2
	s_addc_u32 s53, s53, 0
	v_ashrrev_i32_e32 v11, 31, v10
	v_lshl_add_u64 v[6:7], s[52:53], 0, v[64:65]
	v_lshlrev_b64 v[10:11], 13, v[10:11]
	v_lshl_add_u64 v[12:13], v[6:7], 0, v[10:11]
	v_add_u32_e32 v10, 32, v2
	v_ashrrev_i32_e32 v11, 31, v10
	v_lshlrev_b64 v[10:11], 13, v[10:11]
	v_lshl_add_u64 v[16:17], v[6:7], 0, v[10:11]
	v_add_u32_e32 v10, 40, v2
	v_ashrrev_i32_e32 v11, 31, v10
	v_ashrrev_i32_e32 v3, 31, v2
	v_lshlrev_b64 v[10:11], 13, v[10:11]
	v_lshlrev_b64 v[0:1], 13, v[2:3]
	v_add_u32_e32 v4, 8, v2
	v_add_u32_e32 v8, 16, v2
	v_lshl_add_u64 v[20:21], v[6:7], 0, v[10:11]
	v_add_u32_e32 v10, 48, v2
	v_add_u32_e32 v2, 56, v2
	v_ashrrev_i32_e32 v5, 31, v4
	v_ashrrev_i32_e32 v9, 31, v8
	v_ashrrev_i32_e32 v11, 31, v10
	v_ashrrev_i32_e32 v3, 31, v2
	v_lshlrev_b64 v[4:5], 13, v[4:5]
	v_lshlrev_b64 v[8:9], 13, v[8:9]
	v_lshlrev_b64 v[10:11], 13, v[10:11]
	v_lshlrev_b64 v[2:3], 13, v[2:3]
	v_lshl_add_u64 v[0:1], v[6:7], 0, v[0:1]
	v_lshl_add_u64 v[4:5], v[6:7], 0, v[4:5]
	v_lshl_add_u64 v[8:9], v[6:7], 0, v[8:9]
	v_lshl_add_u64 v[24:25], v[6:7], 0, v[10:11]
	v_lshl_add_u64 v[28:29], v[6:7], 0, v[2:3]
	s_mov_b64 s[86:87], 0

; #define CV_MAP(g_, l_, it_) do { (l_) = lfix; \
;         if (MODE == 2) (it_) = CV_S0 + base + (g_); \
;         else if (MODE == 1) (it_) = cv_ritem(g_); \
;         else if ((g_) < CV_NR) (it_) = cv_ritem(g_); \
;         else { const int q_ = ((g_) - CV_NR) / CV_RPRO; (l_) = 1 + q_; (it_) = cv_ritem(CV_DEFER + ((g_) - CV_NR) - q_ * CV_RPRO); } } while (0)
; __device__ __forceinline__ void p0_item_load(const float* W, int N, int item, int lane, f32x4 (&wv)[8]) {
;     const int nblk = N / 32, kb = item / nblk, nb = item % nblk, k0 = 64 * kb, n0 = 32 * nb;
; #pragma unroll
;     for (int i = 0; i < 8; ++i) wv[i] = *(const f32x4*)(W + (size_t)(k0 + 8 * i + (lane >> 3)) * N + n0 + 4 * (lane & 7));
; }
; template <int MODE>
; __device__ __forceinline__ void cv_jobs(const Frame& F, const Args& a, int lfix, int base, int njobs, int w, int nw) {
;     ...
;         const int g1 = g + nw; int l, it, l1, it1; CV_MAP(g, l, it); CV_MAP(g1, l1, it1);
;         cv_load(a, l, it, F.lane, sa);
;         if (g1 < njobs) cv_load(a, l1, it1, F.lane, sb);
.LBB0_44:
	global_load_dwordx4 v[0:3], v[0:1], off nt
	s_nop 0
	global_load_dwordx4 v[4:7], v[4:5], off nt
	s_nop 0
	global_load_dwordx4 v[8:11], v[8:9], off nt
	s_nop 0
	global_load_dwordx4 v[12:15], v[12:13], off nt
	s_nop 0
	global_load_dwordx4 v[16:19], v[16:17], off nt
	s_nop 0
	global_load_dwordx4 v[20:23], v[20:21], off nt
	s_nop 0
	global_load_dwordx4 v[24:27], v[24:25], off nt
	s_nop 0
	global_load_dwordx4 v[28:31], v[28:29], off nt
	s_mov_b64 s[84:85], -1
	s_and_b64 vcc, exec, s[12:13]
	s_cbranch_vccnz .LBB0_48

; #define LAS __attribute__((address_space(3)))
; __device__ __forceinline__ void p0_prologue(const Frame& F0, const Args& a0) {
;     ...
;         for (int unit = F.vcu; unit < DEPTH * (D6 / 64); unit += F.G) {
;             const int l = unit / (D6 / 64), n0 = (unit % (D6 / 64)) * 64, kp = F.lane >> 4, nq = F.lane & 15;
;             const float* w = a.in[I_WADA] + ((size_t)l * DM + F.wave * 256 + kp) * D6 + n0 + 4 * nq;
;             const LAS float* s = sc + F.wave * 256 + kp;
;             f32x4 a0 = (f32x4){0.f, 0.f, 0.f, 0.f}, a1 = a0, a2 = a0, a3 = a0, a4 = a0;
; #pragma unroll 8
;             for (int k = 0; k < 64; ++k) { const f32x4 wv = *(const f32x4*)(w + (size_t)(4 * k) * D6); a0 += wv * s[4 * k]; a1 += wv * s[DM + 4 * k]; a2 += wv * s[2 * DM + 4 * k]; a3 += wv * s[3 * DM + 4 * k]; a4 += wv * s[4 * DM + 4 * k]; }
.LBB0_104:
	v_lshl_add_u64 v[34:35], v[14:15], 0, s[12:13]
	v_add_co_u32_e64 v42, s[4:5], s22, v34
	ds_read2_b32 v[32:33], v36 offset1:4
	ds_read2_b32 v[30:31], v36 offset0:8 offset1:12
	v_addc_co_u32_e64 v43, s[4:5], 0, v35, s[4:5]
	v_add_co_u32_e64 v52, s[4:5], s23, v34
	ds_read2_b32 v[46:47], v36 offset0:16 offset1:20
	ds_read2_b32 v[76:77], v36 offset0:24 offset1:28
	v_addc_co_u32_e64 v53, s[4:5], 0, v35, s[4:5]
	v_add_co_u32_e64 v56, s[4:5], s24, v34
	global_load_dwordx4 v[38:41], v[34:35], off nt
	s_nop 0
	v_addc_co_u32_e64 v57, s[4:5], 0, v35, s[4:5]
	v_add_co_u32_e64 v60, s[4:5], s25, v34
	v_add_u32_e32 v37, 0x2000, v36
	s_nop 0
	v_addc_co_u32_e64 v61, s[4:5], 0, v35, s[4:5]
	v_add_co_u32_e64 v64, s[4:5], s26, v34
	v_add_u32_e32 v44, 0x4000, v36
	s_nop 0
	v_addc_co_u32_e64 v65, s[4:5], 0, v35, s[4:5]
	v_add_co_u32_e64 v68, s[4:5], s27, v34
	v_add_u32_e32 v45, 0x6000, v36
	s_nop 0
	v_addc_co_u32_e64 v69, s[4:5], 0, v35, s[4:5]
	v_add_co_u32_e64 v34, s[4:5], s28, v34
	v_add_u32_e32 v51, 0x8000, v36
	ds_read2_b32 v[78:79], v37 offset1:4
	ds_read2_b32 v[80:81], v44 offset1:4
	ds_read2_b32 v[82:83], v45 offset1:4
	ds_read2_b32 v[84:85], v51 offset1:4
	ds_read2_b32 v[86:87], v37 offset0:8 offset1:12
	ds_read2_b32 v[88:89], v44 offset0:8 offset1:12
	ds_read2_b32 v[90:91], v45 offset0:8 offset1:12
	ds_read2_b32 v[92:93], v51 offset0:8 offset1:12
	ds_read2_b32 v[94:95], v37 offset0:16 offset1:20
	ds_read2_b32 v[96:97], v44 offset0:16 offset1:20
	ds_read2_b32 v[98:99], v45 offset0:16 offset1:20
	ds_read2_b32 v[100:101], v51 offset0:16 offset1:20
	ds_read2_b32 v[102:103], v37 offset0:24 offset1:28
	ds_read2_b32 v[104:105], v44 offset0:24 offset1:28
	ds_read2_b32 v[106:107], v45 offset0:24 offset1:28
	ds_read2_b32 v[108:109], v51 offset0:24 offset1:28
	v_addc_co_u32_e64 v35, s[4:5], 0, v35, s[4:5]
	global_load_dwordx4 v[42:45], v[42:43], off nt
	s_nop 0
	global_load_dwordx4 v[52:55], v[52:53], off nt
	s_nop 0
	global_load_dwordx4 v[56:59], v[56:57], off nt
	s_nop 0
	global_load_dwordx4 v[60:63], v[60:61], off nt
	s_nop 0
	global_load_dwordx4 v[64:67], v[64:65], off nt
	s_nop 0
	global_load_dwordx4 v[68:71], v[68:69], off nt
	s_nop 0
	global_load_dwordx4 v[72:75], v[34:35], off nt
	s_waitcnt lgkmcnt(14)
	v_mov_b32_e32 v34, v33
	v_mov_b32_e32 v116, v79
	v_mov_b32_e32 v118, v81
	s_waitcnt lgkmcnt(13)
	v_mov_b32_e32 v120, v83
	s_waitcnt lgkmcnt(12)
	v_mov_b32_e32 v122, v85
	v_mov_b32_e32 v110, v31
	s_waitcnt lgkmcnt(11)
	v_mov_b32_e32 v124, v87
	s_waitcnt lgkmcnt(10)
	v_mov_b32_e32 v126, v89
	s_waitcnt lgkmcnt(9)
	v_mov_b32_e32 v128, v91
	s_waitcnt lgkmcnt(8)
	v_mov_b32_e32 v130, v93
	v_mov_b32_e32 v112, v47
	s_waitcnt lgkmcnt(7)
	v_mov_b32_e32 v132, v95
	s_waitcnt lgkmcnt(6)
	v_mov_b32_e32 v134, v97
	s_waitcnt lgkmcnt(5)
	v_mov_b32_e32 v136, v99
	s_waitcnt lgkmcnt(4)
	v_mov_b32_e32 v138, v101
	s_add_u32 s12, s12, 0x180000
	s_addc_u32 s13, s13, 0
	v_mov_b32_e32 v114, v77
	s_waitcnt lgkmcnt(3)
	v_mov_b32_e32 v140, v103
	s_waitcnt lgkmcnt(2)
	v_mov_b32_e32 v142, v105
	s_waitcnt lgkmcnt(1)
	v_mov_b32_e32 v144, v107
	s_waitcnt lgkmcnt(0)
	v_mov_b32_e32 v146, v109
	v_add_u32_e32 v36, 0x80, v36
	s_cmp_lg_u32 s12, 0xc00000
	s_waitcnt vmcnt(7)
	v_pk_fma_f32 v[28:29], v[38:39], v[32:33], v[28:29] op_sel_hi:[1,0,1]
	v_pk_fma_f32 v[18:19], v[40:41], v[32:33], v[18:19] op_sel_hi:[1,0,1]
	v_pk_fma_f32 v[26:27], v[38:39], v[78:79], v[26:27] op_sel_hi:[1,0,1]
	v_pk_fma_f32 v[16:17], v[40:41], v[78:79], v[16:17] op_sel_hi:[1,0,1]
	v_pk_fma_f32 v[24:25], v[38:39], v[80:81], v[24:25] op_sel_hi:[1,0,1]
	v_pk_fma_f32 v[12:13], v[40:41], v[80:81], v[12:13] op_sel_hi:[1,0,1]
	v_pk_fma_f32 v[22:23], v[38:39], v[82:83], v[22:23] op_sel_hi:[1,0,1]
	v_pk_fma_f32 v[10:11], v[40:41], v[82:83], v[10:11] op_sel_hi:[1,0,1]
	v_pk_fma_f32 v[20:21], v[38:39], v[84:85], v[20:21] op_sel_hi:[1,0,1]
	v_pk_fma_f32 v[8:9], v[40:41], v[84:85], v[8:9] op_sel_hi:[1,0,1]
	s_waitcnt vmcnt(6)
	v_pk_fma_f32 v[28:29], v[42:43], v[34:35], v[28:29] op_sel_hi:[1,0,1]
	v_pk_fma_f32 v[18:19], v[44:45], v[34:35], v[18:19] op_sel_hi:[1,0,1]
	v_pk_fma_f32 v[26:27], v[42:43], v[116:117], v[26:27] op_sel_hi:[1,0,1]
	v_pk_fma_f32 v[16:17], v[44:45], v[116:117], v[16:17] op_sel_hi:[1,0,1]
	v_pk_fma_f32 v[24:25], v[42:43], v[118:119], v[24:25] op_sel_hi:[1,0,1]
	v_pk_fma_f32 v[12:13], v[44:45], v[118:119], v[12:13] op_sel_hi:[1,0,1]
	v_pk_fma_f32 v[22:23], v[42:43], v[120:121], v[22:23] op_sel_hi:[1,0,1]
	v_pk_fma_f32 v[10:11], v[44:45], v[120:121], v[10:11] op_sel_hi:[1,0,1]
	v_pk_fma_f32 v[20:21], v[42:43], v[122:123], v[20:21] op_sel_hi:[1,0,1]
	v_pk_fma_f32 v[8:9], v[44:45], v[122:123], v[8:9] op_sel_hi:[1,0,1]
	s_waitcnt vmcnt(5)
	v_pk_fma_f32 v[18:19], v[54:55], v[30:31], v[18:19] op_sel_hi:[1,0,1]
	v_pk_fma_f32 v[28:29], v[52:53], v[30:31], v[28:29] op_sel_hi:[1,0,1]
	v_pk_fma_f32 v[16:17], v[54:55], v[86:87], v[16:17] op_sel_hi:[1,0,1]
	v_pk_fma_f32 v[26:27], v[52:53], v[86:87], v[26:27] op_sel_hi:[1,0,1]
	v_pk_fma_f32 v[12:13], v[54:55], v[88:89], v[12:13] op_sel_hi:[1,0,1]
	v_pk_fma_f32 v[24:25], v[52:53], v[88:89], v[24:25] op_sel_hi:[1,0,1]
	v_pk_fma_f32 v[10:11], v[54:55], v[90:91], v[10:11] op_sel_hi:[1,0,1]
	v_pk_fma_f32 v[22:23], v[52:53], v[90:91], v[22:23] op_sel_hi:[1,0,1]
	v_pk_fma_f32 v[8:9], v[54:55], v[92:93], v[8:9] op_sel_hi:[1,0,1]
	v_pk_fma_f32 v[20:21], v[52:53], v[92:93], v[20:21] op_sel_hi:[1,0,1]
	s_waitcnt vmcnt(4)
; #define LAS __attribute__((address_space(3)))
; __device__ __forceinline__ float shx(float v, int m, int lane) { return __builtin_bit_cast(float, __builtin_amdgcn_ds_bpermute((lane ^ m) << 2, __builtin_bit_cast(int, v))); }
; __device__ __forceinline__ void p0_prologue(const Frame& F0, const Args& a0) {
;     ...
;             for (int k = 0; k < 64; ++k) { const f32x4 wv = *(const f32x4*)(w + (size_t)(4 * k) * D6); a0 += wv * s[4 * k]; a1 += wv * s[DM + 4 * k]; a2 += wv * s[2 * DM + 4 * k]; a3 += wv * s[3 * DM + 4 * k]; a4 += wv * s[4 * DM + 4 * k]; }
; #pragma unroll
;             for (int e = 0; e < 4; ++e) { a0[e] += shx(a0[e], 32, F.lane); a1[e] += shx(a1[e], 32, F.lane); a2[e] += shx(a2[e], 32, F.lane); a3[e] += shx(a3[e], 32, F.lane); a4[e] += shx(a4[e], 32, F.lane);
;                 a0[e] += shx(a0[e], 16, F.lane); a1[e] += shx(a1[e], 16, F.lane); a2[e] += shx(a2[e], 16, F.lane); a3[e] += shx(a3[e], 16, F.lane); a4[e] += shx(a4[e], 16, F.lane); }
;             if (kp == 0) { LAS f32x4* r4 = (LAS f32x4*)red + (F.wave * 5) * 16 + nq; r4[0] = a0; r4[16] = a1; r4[32] = a2; r4[48] = a3; r4[64] = a4; }
	v_pk_fma_f32 v[18:19], v[58:59], v[110:111], v[18:19] op_sel_hi:[1,0,1]
	v_pk_fma_f32 v[28:29], v[56:57], v[110:111], v[28:29] op_sel_hi:[1,0,1]
	v_pk_fma_f32 v[16:17], v[58:59], v[124:125], v[16:17] op_sel_hi:[1,0,1]
	v_pk_fma_f32 v[26:27], v[56:57], v[124:125], v[26:27] op_sel_hi:[1,0,1]
	v_pk_fma_f32 v[12:13], v[58:59], v[126:127], v[12:13] op_sel_hi:[1,0,1]
	v_pk_fma_f32 v[24:25], v[56:57], v[126:127], v[24:25] op_sel_hi:[1,0,1]
	v_pk_fma_f32 v[10:11], v[58:59], v[128:129], v[10:11] op_sel_hi:[1,0,1]
	v_pk_fma_f32 v[22:23], v[56:57], v[128:129], v[22:23] op_sel_hi:[1,0,1]
	v_pk_fma_f32 v[8:9], v[58:59], v[130:131], v[8:9] op_sel_hi:[1,0,1]
	v_pk_fma_f32 v[20:21], v[56:57], v[130:131], v[20:21] op_sel_hi:[1,0,1]
	s_waitcnt vmcnt(3)
	v_pk_fma_f32 v[18:19], v[62:63], v[46:47], v[18:19] op_sel_hi:[1,0,1]
	v_pk_fma_f32 v[28:29], v[60:61], v[46:47], v[28:29] op_sel_hi:[1,0,1]
	v_pk_fma_f32 v[16:17], v[62:63], v[94:95], v[16:17] op_sel_hi:[1,0,1]
	v_pk_fma_f32 v[26:27], v[60:61], v[94:95], v[26:27] op_sel_hi:[1,0,1]
	v_pk_fma_f32 v[12:13], v[62:63], v[96:97], v[12:13] op_sel_hi:[1,0,1]
	v_pk_fma_f32 v[24:25], v[60:61], v[96:97], v[24:25] op_sel_hi:[1,0,1]
	v_pk_fma_f32 v[10:11], v[62:63], v[98:99], v[10:11] op_sel_hi:[1,0,1]
	v_pk_fma_f32 v[22:23], v[60:61], v[98:99], v[22:23] op_sel_hi:[1,0,1]
	v_pk_fma_f32 v[8:9], v[62:63], v[100:101], v[8:9] op_sel_hi:[1,0,1]
	v_pk_fma_f32 v[20:21], v[60:61], v[100:101], v[20:21] op_sel_hi:[1,0,1]
	s_waitcnt vmcnt(2)
	v_pk_fma_f32 v[18:19], v[66:67], v[112:113], v[18:19] op_sel_hi:[1,0,1]
	v_pk_fma_f32 v[28:29], v[64:65], v[112:113], v[28:29] op_sel_hi:[1,0,1]
	v_pk_fma_f32 v[16:17], v[66:67], v[132:133], v[16:17] op_sel_hi:[1,0,1]
	v_pk_fma_f32 v[26:27], v[64:65], v[132:133], v[26:27] op_sel_hi:[1,0,1]
	v_pk_fma_f32 v[12:13], v[66:67], v[134:135], v[12:13] op_sel_hi:[1,0,1]
	v_pk_fma_f32 v[24:25], v[64:65], v[134:135], v[24:25] op_sel_hi:[1,0,1]
	v_pk_fma_f32 v[10:11], v[66:67], v[136:137], v[10:11] op_sel_hi:[1,0,1]
	v_pk_fma_f32 v[22:23], v[64:65], v[136:137], v[22:23] op_sel_hi:[1,0,1]
	v_pk_fma_f32 v[8:9], v[66:67], v[138:139], v[8:9] op_sel_hi:[1,0,1]
	v_pk_fma_f32 v[20:21], v[64:65], v[138:139], v[20:21] op_sel_hi:[1,0,1]
	s_waitcnt vmcnt(1)
	v_pk_fma_f32 v[18:19], v[70:71], v[76:77], v[18:19] op_sel_hi:[1,0,1]
	v_pk_fma_f32 v[28:29], v[68:69], v[76:77], v[28:29] op_sel_hi:[1,0,1]
	v_pk_fma_f32 v[16:17], v[70:71], v[102:103], v[16:17] op_sel_hi:[1,0,1]
	v_pk_fma_f32 v[26:27], v[68:69], v[102:103], v[26:27] op_sel_hi:[1,0,1]
	v_pk_fma_f32 v[12:13], v[70:71], v[104:105], v[12:13] op_sel_hi:[1,0,1]
	v_pk_fma_f32 v[24:25], v[68:69], v[104:105], v[24:25] op_sel_hi:[1,0,1]
	v_pk_fma_f32 v[10:11], v[70:71], v[106:107], v[10:11] op_sel_hi:[1,0,1]
	v_pk_fma_f32 v[22:23], v[68:69], v[106:107], v[22:23] op_sel_hi:[1,0,1]
	v_pk_fma_f32 v[8:9], v[70:71], v[108:109], v[8:9] op_sel_hi:[1,0,1]
	v_pk_fma_f32 v[20:21], v[68:69], v[108:109], v[20:21] op_sel_hi:[1,0,1]
	s_waitcnt vmcnt(0)
	v_pk_fma_f32 v[18:19], v[74:75], v[114:115], v[18:19] op_sel_hi:[1,0,1]
	v_pk_fma_f32 v[28:29], v[72:73], v[114:115], v[28:29] op_sel_hi:[1,0,1]
	v_pk_fma_f32 v[16:17], v[74:75], v[140:141], v[16:17] op_sel_hi:[1,0,1]
	v_pk_fma_f32 v[26:27], v[72:73], v[140:141], v[26:27] op_sel_hi:[1,0,1]
	v_pk_fma_f32 v[12:13], v[74:75], v[142:143], v[12:13] op_sel_hi:[1,0,1]
	v_pk_fma_f32 v[24:25], v[72:73], v[142:143], v[24:25] op_sel_hi:[1,0,1]
	v_pk_fma_f32 v[10:11], v[74:75], v[144:145], v[10:11] op_sel_hi:[1,0,1]
	v_pk_fma_f32 v[22:23], v[72:73], v[144:145], v[22:23] op_sel_hi:[1,0,1]
	v_pk_fma_f32 v[8:9], v[74:75], v[146:147], v[8:9] op_sel_hi:[1,0,1]
	v_pk_fma_f32 v[20:21], v[72:73], v[146:147], v[20:21] op_sel_hi:[1,0,1]
	s_cbranch_scc1 .LBB0_104
	ds_bpermute_b32 v14, v48, v28
	ds_bpermute_b32 v30, v48, v26
	ds_bpermute_b32 v15, v48, v29
	ds_bpermute_b32 v32, v48, v24
	ds_bpermute_b32 v34, v48, v22
	ds_bpermute_b32 v31, v48, v27
	ds_bpermute_b32 v36, v48, v20
	ds_bpermute_b32 v33, v48, v25
	ds_bpermute_b32 v35, v48, v23
	ds_bpermute_b32 v37, v48, v21
	ds_bpermute_b32 v38, v48, v18
	ds_bpermute_b32 v40, v48, v16
	ds_bpermute_b32 v39, v48, v19
	ds_bpermute_b32 v42, v48, v12
	ds_bpermute_b32 v44, v48, v10
	ds_bpermute_b32 v41, v48, v17
	ds_bpermute_b32 v46, v48, v8
	ds_bpermute_b32 v43, v48, v13
	ds_bpermute_b32 v45, v48, v11
	ds_bpermute_b32 v47, v48, v9
	s_waitcnt lgkmcnt(14)
	v_pk_add_f32 v[14:15], v[28:29], v[14:15]
	v_pk_add_f32 v[26:27], v[26:27], v[30:31]
	s_waitcnt lgkmcnt(12)
	v_pk_add_f32 v[24:25], v[24:25], v[32:33]
	s_waitcnt lgkmcnt(11)
	v_pk_add_f32 v[22:23], v[22:23], v[34:35]
	s_waitcnt lgkmcnt(10)
	v_pk_add_f32 v[20:21], v[20:21], v[36:37]
	s_waitcnt lgkmcnt(7)
	v_pk_add_f32 v[18:19], v[18:19], v[38:39]
	s_waitcnt lgkmcnt(4)
	v_pk_add_f32 v[16:17], v[16:17], v[40:41]
	s_waitcnt lgkmcnt(2)
	v_pk_add_f32 v[12:13], v[12:13], v[42:43]
	s_waitcnt lgkmcnt(1)
	v_pk_add_f32 v[10:11], v[10:11], v[44:45]
	s_waitcnt lgkmcnt(0)
	v_pk_add_f32 v[8:9], v[8:9], v[46:47]
	ds_bpermute_b32 v28, v49, v14
	ds_bpermute_b32 v30, v49, v26
	ds_bpermute_b32 v32, v49, v24
	ds_bpermute_b32 v34, v49, v22
	ds_bpermute_b32 v36, v49, v20
	ds_bpermute_b32 v29, v49, v15
	ds_bpermute_b32 v31, v49, v27
	ds_bpermute_b32 v33, v49, v25
	ds_bpermute_b32 v35, v49, v23
	ds_bpermute_b32 v37, v49, v21
	ds_bpermute_b32 v38, v49, v18
	ds_bpermute_b32 v40, v49, v16
	ds_bpermute_b32 v42, v49, v12
	ds_bpermute_b32 v44, v49, v10
	ds_bpermute_b32 v46, v49, v8
	ds_bpermute_b32 v39, v49, v19
	ds_bpermute_b32 v41, v49, v17
	ds_bpermute_b32 v43, v49, v13
	ds_bpermute_b32 v45, v49, v11
	ds_bpermute_b32 v47, v49, v9
	s_and_saveexec_b64 s[4:5], vcc
	s_cbranch_execz .LBB0_107
	s_waitcnt lgkmcnt(10)
	v_pk_add_f32 v[52:53], v[20:21], v[36:37]
	v_pk_add_f32 v[20:21], v[24:25], v[32:33]
	s_waitcnt lgkmcnt(3)
	v_pk_add_f32 v[32:33], v[16:17], v[40:41]
	v_pk_add_f32 v[16:17], v[18:19], v[38:39]
	v_pk_add_f32 v[14:15], v[14:15], v[28:29]
	s_waitcnt lgkmcnt(0)
	v_pk_add_f32 v[54:55], v[8:9], v[46:47]
	v_pk_add_f32 v[10:11], v[10:11], v[44:45]
	v_pk_add_f32 v[8:9], v[22:23], v[34:35]
	v_pk_add_f32 v[22:23], v[12:13], v[42:43]
	v_pk_add_f32 v[30:31], v[26:27], v[30:31]
	ds_write_b128 v50, v[14:17] offset:49152
	ds_write_b128 v50, v[30:33] offset:49408
	ds_write_b128 v50, v[20:23] offset:49664
	ds_write_b128 v50, v[8:11] offset:49920
	ds_write_b128 v50, v[52:55] offset:50176

; #define CV_MAP(g_, l_, it_) do { (l_) = lfix; \
;         if (MODE == 2) (it_) = CV_S0 + base + (g_); \
;         else if (MODE == 1) (it_) = cv_ritem(g_); \
;         else if ((g_) < CV_NR) (it_) = cv_ritem(g_); \
;         else { const int q_ = ((g_) - CV_NR) / CV_RPRO; (l_) = 1 + q_; (it_) = cv_ritem(CV_DEFER + ((g_) - CV_NR) - q_ * CV_RPRO); } } while (0)
; __device__ __forceinline__ void cv_load(const Args& a, int l, int it, int lane, f32x4 (&wv)[8]) {
;     ...
;     else if (it < CV_B) p0_item_load(a.in[I_WOUT] + (size_t)l * DM * DM, DM, it - CV_A, lane, wv);
;     else if (it < CV_C) p0_item_load(a.in[I_W1] + (size_t)l * DM * DFF, DFF, it - CV_B, lane, wv);
;     else p0_item_load(a.in[I_W2] + (size_t)l * DFF * DM, DM, it - CV_C, lane, wv);
; }
; template <int MODE>
; __device__ __forceinline__ void cv_jobs(const Frame& F, const Args& a, int lfix, int base, int njobs, int w, int nw) {
;     ...
;     for (int g = w; g < njobs; g += 2 * nw) {
;         const int g1 = g + nw; int l, it, l1, it1; CV_MAP(g, l, it); CV_MAP(g1, l1, it1);
;         cv_load(a, l, it, F.lane, sa);
;         if (g1 < njobs) cv_load(a, l1, it1, F.lane, sb);
;         cv_store(a, sa, scr, l, it, F.lane);
;         if (g1 < njobs) cv_store(a, sb, scr, l1, it1, F.lane);
;     }
.LBB0_478:
	s_add_i32 s7, s8, 0x800
	s_add_i32 s10, s8, 0x27e0
	s_cmpk_gt_i32 s7, 0xf63f
	s_cselect_b64 s[2:3], -1, 0
	s_mov_b64 s[0:1], -1
	s_and_b64 vcc, exec, s[2:3]
	s_cbranch_vccz .LBB0_484
	s_cmpk_gt_u32 s10, 0x1e1f
	s_cbranch_scc0 .LBB0_481
	s_add_i32 s0, s8, 0x9c0
	s_bfe_u32 s0, s0, 0x80008
	s_add_i32 s1, s6, 0xffffb800
	s_and_b32 s1, s1, 0x1fe0
	s_waitcnt vmcnt(6)
	v_lshl_add_u32 v32, s0, 6, v76
	s_lshl_b32 s84, s1, 2
	v_ashrrev_i32_e32 v33, 31, v32
	v_lshl_add_u64 v[34:35], v[64:65], 0, s[84:85]
	v_lshlrev_b64 v[32:33], 15, v[32:33]
	s_waitcnt vmcnt(0)
	v_lshl_add_u64 v[60:61], v[34:35], 0, v[32:33]
	v_add_co_u32_e32 v32, vcc, 0x40000, v60
	s_mov_b64 s[0:1], 0
	s_nop 0
	v_addc_co_u32_e32 v33, vcc, 0, v61, vcc
	v_add_co_u32_e32 v40, vcc, 0x80000, v60
	global_load_dwordx4 v[36:39], v[60:61], off nt
	s_nop 0
	global_load_dwordx4 v[32:35], v[32:33], off nt
	v_addc_co_u32_e32 v41, vcc, 0, v61, vcc
	v_add_co_u32_e32 v42, vcc, 0xc0000, v60
	s_nop 1
	v_addc_co_u32_e32 v43, vcc, 0, v61, vcc
	v_add_co_u32_e32 v48, vcc, s73, v60
	global_load_dwordx4 v[44:47], v[40:41], off nt
	s_nop 0
	global_load_dwordx4 v[40:43], v[42:43], off nt
	v_addc_co_u32_e32 v49, vcc, 0, v61, vcc
	v_add_co_u32_e32 v50, vcc, 0x140000, v60
	s_nop 1
	v_addc_co_u32_e32 v51, vcc, 0, v61, vcc
	v_add_co_u32_e32 v56, vcc, 0x180000, v60
	global_load_dwordx4 v[52:55], v[48:49], off nt
	s_nop 0
	global_load_dwordx4 v[48:51], v[50:51], off nt
	v_addc_co_u32_e32 v57, vcc, 0, v61, vcc
	global_load_dwordx4 v[56:59], v[56:57], off nt
	v_lshl_add_u64 v[60:61], v[60:61], 0, s[14:15]
.LBB0_481:
	s_andn2_b64 vcc, exec, s[0:1]
	s_cbranch_vccnz .LBB0_483
	s_add_i32 s0, s8, 0x11c0
	s_and_b32 s0, s0, 0xffc0
	s_add_i32 s1, s6, 0xb800
	s_and_b32 s1, s1, 0x7e0
	s_waitcnt vmcnt(5)
	v_add_u32_e32 v32, s0, v76
	s_lshl_b32 s84, s1, 2
	v_ashrrev_i32_e32 v33, 31, v32
	v_lshl_add_u64 v[34:35], v[66:67], 0, s[84:85]
	v_lshlrev_b64 v[32:33], 13, v[32:33]
	s_waitcnt vmcnt(0)
	v_lshl_add_u64 v[60:61], v[34:35], 0, v[32:33]
	v_add_co_u32_e32 v32, vcc, 0x10000, v60
	s_nop 1
	v_addc_co_u32_e32 v33, vcc, 0, v61, vcc
	s_waitcnt vmcnt(3)
	v_add_co_u32_e32 v40, vcc, 0x20000, v60
	global_load_dwordx4 v[36:39], v[60:61], off nt
	s_nop 0
	global_load_dwordx4 v[32:35], v[32:33], off nt
	v_addc_co_u32_e32 v41, vcc, 0, v61, vcc
	v_add_co_u32_e32 v42, vcc, 0x30000, v60
	s_nop 1
	v_addc_co_u32_e32 v43, vcc, 0, v61, vcc
	s_waitcnt vmcnt(3)
	v_add_co_u32_e32 v48, vcc, s90, v60
	global_load_dwordx4 v[44:47], v[40:41], off nt
	s_nop 0
	global_load_dwordx4 v[40:43], v[42:43], off nt
	v_addc_co_u32_e32 v49, vcc, 0, v61, vcc
	v_add_co_u32_e32 v50, vcc, 0x50000, v60
	s_nop 1
	v_addc_co_u32_e32 v51, vcc, 0, v61, vcc
	s_waitcnt vmcnt(4)
	v_add_co_u32_e32 v56, vcc, 0x60000, v60
	global_load_dwordx4 v[52:55], v[48:49], off nt
	s_nop 0
	global_load_dwordx4 v[48:51], v[50:51], off nt
	v_addc_co_u32_e32 v57, vcc, 0, v61, vcc
	global_load_dwordx4 v[56:59], v[56:57], off nt
	v_lshl_add_u64 v[60:61], v[60:61], 0, s[16:17]

; #define CV_MAP(g_, l_, it_) do { (l_) = lfix; \
;         if (MODE == 2) (it_) = CV_S0 + base + (g_); \
;         else if (MODE == 1) (it_) = cv_ritem(g_); \
;         else if ((g_) < CV_NR) (it_) = cv_ritem(g_); \
;         else { const int q_ = ((g_) - CV_NR) / CV_RPRO; (l_) = 1 + q_; (it_) = cv_ritem(CV_DEFER + ((g_) - CV_NR) - q_ * CV_RPRO); } } while (0)
; __device__ __forceinline__ void cv_load(const Args& a, int l, int it, int lane, f32x4 (&wv)[8]) {
;     ...
;     else if (it < CV_B) p0_item_load(a.in[I_WOUT] + (size_t)l * DM * DM, DM, it - CV_A, lane, wv);
;     else if (it < CV_C) p0_item_load(a.in[I_W1] + (size_t)l * DM * DFF, DFF, it - CV_B, lane, wv);
;     else p0_item_load(a.in[I_W2] + (size_t)l * DFF * DM, DM, it - CV_C, lane, wv);
; }
; template <int MODE>
; __device__ __forceinline__ void cv_jobs(const Frame& F, const Args& a, int lfix, int base, int njobs, int w, int nw) {
;     ...
;     for (int g = w; g < njobs; g += 2 * nw) {
;         const int g1 = g + nw; int l, it, l1, it1; CV_MAP(g, l, it); CV_MAP(g1, l1, it1);
;         cv_load(a, l, it, F.lane, sa);
;         if (g1 < njobs) cv_load(a, l1, it1, F.lane, sb);
;         cv_store(a, sa, scr, l, it, F.lane);
;         if (g1 < njobs) cv_store(a, sb, scr, l1, it1, F.lane);
;     }
.LBB0_484:
	s_andn2_b64 vcc, exec, s[0:1]
	s_mul_hi_i32 s11, s10, 0xb92143fb
	s_cbranch_vccnz .LBB0_486
	s_add_i32 s0, s11, s10
	s_lshr_b32 s1, s0, 31
	s_ashr_i32 s0, s0, 7
	s_add_i32 s1, s0, s1
	s_mul_i32 s0, s1, 0xb1
	s_sub_i32 s0, s10, s0
	s_lshl_b32 s0, s0, 5
	s_waitcnt vmcnt(0)
	v_lshl_add_u32 v62, s1, 6, v76
	s_ashr_i32 s1, s0, 31
	v_lshl_add_u64 v[60:61], s[0:1], 2, v[68:69]
	s_waitcnt vmcnt(5)
	v_add_u32_e32 v34, 8, v62
	s_waitcnt vmcnt(3)
	v_add_u32_e32 v40, 16, v62
	v_add_u32_e32 v42, 24, v62
	s_waitcnt vmcnt(1)
	v_add_u32_e32 v48, 32, v62
	v_add_u32_e32 v50, 40, v62
	s_waitcnt vmcnt(0)
	v_add_u32_e32 v56, 48, v62
	v_mad_i64_i32 v[32:33], s[0:1], v62, s12, v[60:61]
	v_mad_i64_i32 v[34:35], s[0:1], v34, s12, v[60:61]
	v_mad_i64_i32 v[40:41], s[0:1], v40, s12, v[60:61]
	v_mad_i64_i32 v[42:43], s[0:1], v42, s12, v[60:61]
	v_mad_i64_i32 v[48:49], s[0:1], v48, s12, v[60:61]
	v_mad_i64_i32 v[50:51], s[0:1], v50, s12, v[60:61]
	v_mad_i64_i32 v[56:57], s[0:1], v56, s12, v[60:61]
	global_load_dwordx4 v[36:39], v[32:33], off nt
	s_nop 0
	global_load_dwordx4 v[32:35], v[34:35], off nt
	s_nop 0
	global_load_dwordx4 v[44:47], v[40:41], off nt
	s_nop 0
	global_load_dwordx4 v[40:43], v[42:43], off nt
	s_nop 0
	global_load_dwordx4 v[52:55], v[48:49], off nt
	s_nop 0
	global_load_dwordx4 v[48:51], v[50:51], off nt
	v_add_u32_e32 v62, 56, v62
	global_load_dwordx4 v[56:59], v[56:57], off nt
	v_mad_i64_i32 v[60:61], s[0:1], v62, s12, v[60:61]
.LBB0_486:
	s_waitcnt vmcnt(0)
	global_load_dwordx4 v[60:63], v[60:61], off nt
	s_add_i32 s9, s8, 0x2be0
	s_cmpk_lt_i32 s7, 0xc00
	s_cselect_b64 s[0:1], -1, 0
	s_cmpk_gt_i32 s7, 0xbff
	s_cbranch_scc1 .LBB0_498
	s_cmpk_gt_i32 s7, 0xf23f
	s_mov_b64 s[4:5], -1
	s_cbranch_scc0 .LBB0_493
	s_cmpk_gt_u32 s9, 0x1e1f
	s_cbranch_scc0 .LBB0_490
	s_add_i32 s4, s8, 0xdc0
	s_bfe_u32 s4, s4, 0x80008
	s_add_i32 s5, s6, 0x3800
	s_and_b32 s5, s5, 0x1fe0
	v_lshl_add_u32 v0, s4, 6, v76
	s_lshl_b32 s84, s5, 2
	v_ashrrev_i32_e32 v1, 31, v0
	v_lshl_add_u64 v[2:3], v[64:65], 0, s[84:85]
	v_lshlrev_b64 v[0:1], 15, v[0:1]
	v_lshl_add_u64 v[0:1], v[2:3], 0, v[0:1]
	s_mov_b64 s[4:5], 0x80000
	v_lshl_add_u64 v[8:9], v[0:1], 0, s[4:5]
	s_mov_b64 s[4:5], 0xc0000
	v_lshl_add_u64 v[12:13], v[0:1], 0, s[4:5]
	s_mov_b64 s[4:5], 0x100000
	v_lshl_add_u64 v[16:17], v[0:1], 0, s[4:5]
	s_mov_b64 s[4:5], 0x140000
	v_lshl_add_u64 v[20:21], v[0:1], 0, s[4:5]
	s_mov_b64 s[4:5], 0x180000
	v_lshl_add_u64 v[4:5], v[0:1], 0, s[88:89]
	v_lshl_add_u64 v[24:25], v[0:1], 0, s[4:5]
	v_lshl_add_u64 v[28:29], v[0:1], 0, s[14:15]
	s_mov_b64 s[4:5], 0

; #define CV_MAP(g_, l_, it_) do { (l_) = lfix; \
;         if (MODE == 2) (it_) = CV_S0 + base + (g_); \
;         else if (MODE == 1) (it_) = cv_ritem(g_); \
;         else if ((g_) < CV_NR) (it_) = cv_ritem(g_); \
;         else { const int q_ = ((g_) - CV_NR) / CV_RPRO; (l_) = 1 + q_; (it_) = cv_ritem(CV_DEFER + ((g_) - CV_NR) - q_ * CV_RPRO); } } while (0)
; __device__ __forceinline__ void p0_item_load(const float* W, int N, int item, int lane, f32x4 (&wv)[8]) {
;     const int nblk = N / 32, kb = item / nblk, nb = item % nblk, k0 = 64 * kb, n0 = 32 * nb;
; #pragma unroll
;     for (int i = 0; i < 8; ++i) wv[i] = *(const f32x4*)(W + (size_t)(k0 + 8 * i + (lane >> 3)) * N + n0 + 4 * (lane & 7));
; }
; template <int MODE>
; __device__ __forceinline__ void cv_jobs(const Frame& F, const Args& a, int lfix, int base, int njobs, int w, int nw) {
;     ...
;         const int g1 = g + nw; int l, it, l1, it1; CV_MAP(g, l, it); CV_MAP(g1, l1, it1);
;         cv_load(a, l, it, F.lane, sa);
;         if (g1 < njobs) cv_load(a, l1, it1, F.lane, sb);
.LBB0_495:
	global_load_dwordx4 v[0:3], v[0:1], off nt
	s_nop 0
	global_load_dwordx4 v[4:7], v[4:5], off nt
	s_nop 0
	global_load_dwordx4 v[8:11], v[8:9], off nt
	s_nop 0
	global_load_dwordx4 v[12:15], v[12:13], off nt
	s_nop 0
	global_load_dwordx4 v[16:19], v[16:17], off nt
	s_nop 0
	global_load_dwordx4 v[20:23], v[20:21], off nt
	s_nop 0
	global_load_dwordx4 v[24:27], v[24:25], off nt
	s_nop 0
	global_load_dwordx4 v[28:31], v[28:29], off nt
	s_mov_b64 s[4:5], -1
	s_and_b64 vcc, exec, s[2:3]
	s_cbranch_vccnz .LBB0_499

; #define CV_MAP(g_, l_, it_) do { (l_) = lfix; \
;         if (MODE == 2) (it_) = CV_S0 + base + (g_); \
;         else if (MODE == 1) (it_) = cv_ritem(g_); \
;         else if ((g_) < CV_NR) (it_) = cv_ritem(g_); \
;         else { const int q_ = ((g_) - CV_NR) / CV_RPRO; (l_) = 1 + q_; (it_) = cv_ritem(CV_DEFER + ((g_) - CV_NR) - q_ * CV_RPRO); } } while (0)
; __device__ __forceinline__ void cv_load(const Args& a, int l, int it, int lane, f32x4 (&wv)[8]) {
;     ...
;     else if (it < CV_B) p0_item_load(a.in[I_WOUT] + (size_t)l * DM * DM, DM, it - CV_A, lane, wv);
;     else if (it < CV_C) p0_item_load(a.in[I_W1] + (size_t)l * DM * DFF, DFF, it - CV_B, lane, wv);
;     else p0_item_load(a.in[I_W2] + (size_t)l * DFF * DM, DM, it - CV_C, lane, wv);
; }
; template <int MODE>
; __device__ __forceinline__ void cv_jobs(const Frame& F, const Args& a, int lfix, int base, int njobs, int w, int nw) {
;     ...
;     for (int g = w; g < njobs; g += 2 * nw) {
;         const int g1 = g + nw; int l, it, l1, it1; CV_MAP(g, l, it); CV_MAP(g1, l1, it1);
;         cv_load(a, l, it, F.lane, sa);
;         if (g1 < njobs) cv_load(a, l1, it1, F.lane, sb);
;         cv_store(a, sa, scr, l, it, F.lane);
;         if (g1 < njobs) cv_store(a, sb, scr, l1, it1, F.lane);
;     }
.LBB0_652:
	s_add_i32 s8, s6, 0xffffe640
	s_add_i32 s10, s6, 0x1620
	s_cmpk_gt_i32 s8, 0xe63f
	s_cselect_b64 s[2:3], -1, 0
	s_mov_b64 s[0:1], -1
	s_and_b64 vcc, exec, s[2:3]
	s_cbranch_vccz .LBB0_658
	s_cmpk_gt_u32 s10, 0x1e1f
	s_cbranch_scc0 .LBB0_655
	s_add_i32 s0, s6, 0xfffff800
	s_bfe_u32 s0, s0, 0x80008
	s_add_i32 s1, s7, 0x18400
	s_and_b32 s1, s1, 0x1fe0
	s_waitcnt vmcnt(6)
	v_lshl_add_u32 v32, s0, 6, v76
	s_lshl_b32 s84, s1, 2
	v_ashrrev_i32_e32 v33, 31, v32
	v_lshl_add_u64 v[34:35], v[64:65], 0, s[84:85]
	v_lshlrev_b64 v[32:33], 15, v[32:33]
	s_waitcnt vmcnt(0)
	v_lshl_add_u64 v[60:61], v[34:35], 0, v[32:33]
	v_add_co_u32_e32 v32, vcc, 0x40000, v60
	s_mov_b64 s[0:1], 0
	s_nop 0
	v_addc_co_u32_e32 v33, vcc, 0, v61, vcc
	v_add_co_u32_e32 v40, vcc, 0x80000, v60
	global_load_dwordx4 v[36:39], v[60:61], off nt
	s_nop 0
	global_load_dwordx4 v[32:35], v[32:33], off nt
	v_addc_co_u32_e32 v41, vcc, 0, v61, vcc
	v_add_co_u32_e32 v42, vcc, 0xc0000, v60
	s_nop 1
	v_addc_co_u32_e32 v43, vcc, 0, v61, vcc
	s_waitcnt vmcnt(11)
	v_add_co_u32_e32 v48, vcc, s73, v60
	global_load_dwordx4 v[44:47], v[40:41], off nt
	s_nop 0
	global_load_dwordx4 v[40:43], v[42:43], off nt
	v_addc_co_u32_e32 v49, vcc, 0, v61, vcc
	v_add_co_u32_e32 v50, vcc, 0x140000, v60
	s_nop 1
	v_addc_co_u32_e32 v51, vcc, 0, v61, vcc
	s_waitcnt vmcnt(12)
	v_add_co_u32_e32 v56, vcc, 0x180000, v60
	global_load_dwordx4 v[52:55], v[48:49], off nt
	s_nop 0
	global_load_dwordx4 v[48:51], v[50:51], off nt
	v_addc_co_u32_e32 v57, vcc, 0, v61, vcc
	global_load_dwordx4 v[56:59], v[56:57], off nt
	v_lshl_add_u64 v[60:61], v[60:61], 0, s[14:15]
.LBB0_655:
	s_andn2_b64 vcc, exec, s[0:1]
	s_cbranch_vccnz .LBB0_657
	s_and_b32 s0, s6, 0xffc0
	s_add_i32 s1, s7, 0x28400
	s_and_b32 s1, s1, 0x7e0
	s_waitcnt vmcnt(5)
	v_add_u32_e32 v32, s0, v76
	s_lshl_b32 s84, s1, 2
	v_ashrrev_i32_e32 v33, 31, v32
	v_lshl_add_u64 v[34:35], v[66:67], 0, s[84:85]
	v_lshlrev_b64 v[32:33], 13, v[32:33]
	s_waitcnt vmcnt(0)
	v_lshl_add_u64 v[60:61], v[34:35], 0, v[32:33]
	v_add_co_u32_e32 v32, vcc, 0x10000, v60
	s_nop 1
	v_addc_co_u32_e32 v33, vcc, 0, v61, vcc
	s_waitcnt vmcnt(3)
	v_add_co_u32_e32 v40, vcc, 0x20000, v60
	global_load_dwordx4 v[36:39], v[60:61], off nt
	s_nop 0
	global_load_dwordx4 v[32:35], v[32:33], off nt
	v_addc_co_u32_e32 v41, vcc, 0, v61, vcc
	v_add_co_u32_e32 v42, vcc, 0x30000, v60
	s_nop 1
	v_addc_co_u32_e32 v43, vcc, 0, v61, vcc
	s_waitcnt vmcnt(3)
	v_add_co_u32_e32 v48, vcc, s90, v60
	global_load_dwordx4 v[44:47], v[40:41], off nt
	s_nop 0
	global_load_dwordx4 v[40:43], v[42:43], off nt
	v_addc_co_u32_e32 v49, vcc, 0, v61, vcc
	v_add_co_u32_e32 v50, vcc, 0x50000, v60
	s_nop 1
	v_addc_co_u32_e32 v51, vcc, 0, v61, vcc
	s_waitcnt vmcnt(4)
	v_add_co_u32_e32 v56, vcc, 0x60000, v60
	global_load_dwordx4 v[52:55], v[48:49], off nt
	s_nop 0
	global_load_dwordx4 v[48:51], v[50:51], off nt
	v_addc_co_u32_e32 v57, vcc, 0, v61, vcc
	global_load_dwordx4 v[56:59], v[56:57], off nt
	v_lshl_add_u64 v[60:61], v[60:61], 0, s[16:17]

; #define CV_MAP(g_, l_, it_) do { (l_) = lfix; \
;         if (MODE == 2) (it_) = CV_S0 + base + (g_); \
;         else if (MODE == 1) (it_) = cv_ritem(g_); \
;         else if ((g_) < CV_NR) (it_) = cv_ritem(g_); \
;         else { const int q_ = ((g_) - CV_NR) / CV_RPRO; (l_) = 1 + q_; (it_) = cv_ritem(CV_DEFER + ((g_) - CV_NR) - q_ * CV_RPRO); } } while (0)
; __device__ __forceinline__ void cv_load(const Args& a, int l, int it, int lane, f32x4 (&wv)[8]) {
;     ...
;     else if (it < CV_B) p0_item_load(a.in[I_WOUT] + (size_t)l * DM * DM, DM, it - CV_A, lane, wv);
;     else if (it < CV_C) p0_item_load(a.in[I_W1] + (size_t)l * DM * DFF, DFF, it - CV_B, lane, wv);
;     else p0_item_load(a.in[I_W2] + (size_t)l * DFF * DM, DM, it - CV_C, lane, wv);
; }
; template <int MODE>
; __device__ __forceinline__ void cv_jobs(const Frame& F, const Args& a, int lfix, int base, int njobs, int w, int nw) {
;     ...
;     for (int g = w; g < njobs; g += 2 * nw) {
;         const int g1 = g + nw; int l, it, l1, it1; CV_MAP(g, l, it); CV_MAP(g1, l1, it1);
;         cv_load(a, l, it, F.lane, sa);
;         if (g1 < njobs) cv_load(a, l1, it1, F.lane, sb);
;         cv_store(a, sa, scr, l, it, F.lane);
;         if (g1 < njobs) cv_store(a, sb, scr, l1, it1, F.lane);
;     }
.LBB0_660:
	s_waitcnt vmcnt(0)
	global_load_dwordx4 v[60:63], v[60:61], off nt
	s_add_i32 s9, s6, 0x1880
	s_cmpk_lt_i32 s8, 0xbe0
	s_cselect_b64 s[0:1], -1, 0
	s_cmpk_gt_i32 s8, 0xbdf
	s_cbranch_scc1 .LBB0_672
	s_cmpk_gt_i32 s8, 0xe3df
	s_mov_b64 s[4:5], -1
	s_cbranch_scc0 .LBB0_667
	s_cmpk_gt_u32 s9, 0x1e1f
	s_cbranch_scc0 .LBB0_664
	s_add_i32 s4, s6, 0xfffffa60
	s_bfe_u32 s4, s4, 0x80008
	s_add_i32 s5, s7, 0x1d000
	s_and_b32 s5, s5, 0x1fe0
	v_lshl_add_u32 v0, s4, 6, v76
	s_lshl_b32 s84, s5, 2
	v_ashrrev_i32_e32 v1, 31, v0
	v_lshl_add_u64 v[2:3], v[64:65], 0, s[84:85]
	v_lshlrev_b64 v[0:1], 15, v[0:1]
	v_lshl_add_u64 v[0:1], v[2:3], 0, v[0:1]
	s_mov_b64 s[4:5], 0x80000
	v_lshl_add_u64 v[8:9], v[0:1], 0, s[4:5]
	s_mov_b64 s[4:5], 0xc0000
	v_lshl_add_u64 v[12:13], v[0:1], 0, s[4:5]
	s_mov_b64 s[4:5], 0x100000
	v_lshl_add_u64 v[16:17], v[0:1], 0, s[4:5]
	s_mov_b64 s[4:5], 0x140000
	v_lshl_add_u64 v[20:21], v[0:1], 0, s[4:5]
	s_mov_b64 s[4:5], 0x180000
	v_lshl_add_u64 v[4:5], v[0:1], 0, s[88:89]
	v_lshl_add_u64 v[24:25], v[0:1], 0, s[4:5]
	v_lshl_add_u64 v[28:29], v[0:1], 0, s[14:15]
	s_mov_b64 s[4:5], 0

; #define LAS __attribute__((address_space(3)))
; #define CV_MAP(g_, l_, it_) do { (l_) = lfix; \
;         if (MODE == 2) (it_) = CV_S0 + base + (g_); \
;         else if (MODE == 1) (it_) = cv_ritem(g_); \
;         else if ((g_) < CV_NR) (it_) = cv_ritem(g_); \
;         else { const int q_ = ((g_) - CV_NR) / CV_RPRO; (l_) = 1 + q_; (it_) = cv_ritem(CV_DEFER + ((g_) - CV_NR) - q_ * CV_RPRO); } } while (0)
; __device__ __forceinline__ void cv_load(const Args& a, int l, int it, int lane, f32x4 (&wv)[8]) {
;     ...
;     else if (it < CV_B) p0_item_load(a.in[I_WOUT] + (size_t)l * DM * DM, DM, it - CV_A, lane, wv);
;     else if (it < CV_C) p0_item_load(a.in[I_W1] + (size_t)l * DM * DFF, DFF, it - CV_B, lane, wv);
;     else p0_item_load(a.in[I_W2] + (size_t)l * DFF * DM, DM, it - CV_C, lane, wv);
; }
; template <int MODE>
; __device__ __forceinline__ void cv_jobs(const Frame& F, const Args& a, int lfix, int base, int njobs, int w, int nw) {
;     LAS float* scr = (LAS float*)(F.lds + RING_OFF + F.wave * 16384);
;     f32x4 sa[8], sb[8];
;     ...
;     for (int g = w; g < njobs; g += 2 * nw) {
;         const int g1 = g + nw; int l, it, l1, it1; CV_MAP(g, l, it); CV_MAP(g1, l1, it1);
;         cv_load(a, l, it, F.lane, sa);
;         if (g1 < njobs) cv_load(a, l1, it1, F.lane, sb);
.LBB0_985:
	s_add_i32 s9, s8, 0x3e20
	s_add_i32 s2, s8, 0x5c60
	s_cmpk_lt_i32 s9, 0x1fe0
	s_cselect_b32 s10, s9, s2
	s_cmpk_gt_i32 s10, 0x161f
	s_cselect_b64 s[2:3], -1, 0
	s_mov_b64 s[4:5], -1
	s_and_b64 vcc, exec, s[2:3]
	s_cbranch_vccz .LBB0_995
	s_cmpk_gt_u32 s10, 0x1e1f
	s_cbranch_scc0 .LBB0_992
	s_cmpk_gt_u32 s10, 0x3e1f
	s_cbranch_scc0 .LBB0_989
	s_add_i32 s4, s10, 0xffffc1e0
	s_and_b32 s5, s4, 0xffffffc0
	s_waitcnt vmcnt(6)
	v_add_u32_e32 v32, s5, v80
	s_lshl_b32 s4, s4, 7
	s_and_b32 s84, s4, 0x1f80
	v_ashrrev_i32_e32 v33, 31, v32
	v_lshl_add_u64 v[34:35], v[64:65], 0, s[84:85]
	v_lshlrev_b64 v[32:33], 13, v[32:33]
	s_waitcnt vmcnt(0)
	v_lshl_add_u64 v[60:61], v[34:35], 0, v[32:33]
	v_add_co_u32_e32 v32, vcc, 0x10000, v60
	s_mov_b64 s[4:5], 0
	s_nop 0
	v_addc_co_u32_e32 v33, vcc, 0, v61, vcc
	v_add_co_u32_e32 v40, vcc, 0x20000, v60
	global_load_dwordx4 v[36:39], v[60:61], off nt
	s_nop 0
	global_load_dwordx4 v[32:35], v[32:33], off nt
	v_addc_co_u32_e32 v41, vcc, 0, v61, vcc
	v_add_co_u32_e32 v42, vcc, 0x30000, v60
	s_nop 1
	v_addc_co_u32_e32 v43, vcc, 0, v61, vcc
	v_add_co_u32_e32 v48, vcc, s90, v60
	global_load_dwordx4 v[44:47], v[40:41], off nt
	s_nop 0
	global_load_dwordx4 v[40:43], v[42:43], off nt
	v_addc_co_u32_e32 v49, vcc, 0, v61, vcc
	v_add_co_u32_e32 v50, vcc, 0x50000, v60
	s_nop 1
	v_addc_co_u32_e32 v51, vcc, 0, v61, vcc
	v_add_co_u32_e32 v56, vcc, 0x60000, v60
	global_load_dwordx4 v[52:55], v[48:49], off nt
	s_nop 0
	global_load_dwordx4 v[48:51], v[50:51], off nt
	v_addc_co_u32_e32 v57, vcc, 0, v61, vcc
	global_load_dwordx4 v[56:59], v[56:57], off nt
	v_lshl_add_u64 v[60:61], v[60:61], 0, s[18:19]
.LBB0_989:
	s_andn2_b64 vcc, exec, s[4:5]
	s_cbranch_vccnz .LBB0_991
	s_add_i32 s4, s10, 0xffffe1e0
	s_bfe_u32 s5, s4, 0x80008
	s_waitcnt vmcnt(5)
	v_lshl_add_u32 v32, s5, 6, v80
	s_lshl_b32 s4, s4, 7
	s_and_b32 s84, s4, 0x7f80
	v_ashrrev_i32_e32 v33, 31, v32
	v_lshl_add_u64 v[34:35], v[66:67], 0, s[84:85]
	v_lshlrev_b64 v[32:33], 15, v[32:33]
	s_waitcnt vmcnt(0)
	v_lshl_add_u64 v[60:61], v[34:35], 0, v[32:33]
	v_add_co_u32_e32 v32, vcc, 0x40000, v60
	s_nop 1
	v_addc_co_u32_e32 v33, vcc, 0, v61, vcc
	s_waitcnt vmcnt(3)
	v_add_co_u32_e32 v40, vcc, 0x80000, v60
	global_load_dwordx4 v[36:39], v[60:61], off nt
	s_nop 0
	global_load_dwordx4 v[32:35], v[32:33], off nt
	v_addc_co_u32_e32 v41, vcc, 0, v61, vcc
	v_add_co_u32_e32 v42, vcc, 0xc0000, v60
	s_nop 1
	v_addc_co_u32_e32 v43, vcc, 0, v61, vcc
	s_waitcnt vmcnt(3)
	v_add_co_u32_e32 v48, vcc, s73, v60
	global_load_dwordx4 v[44:47], v[40:41], off nt
	s_nop 0
	global_load_dwordx4 v[40:43], v[42:43], off nt
	v_addc_co_u32_e32 v49, vcc, 0, v61, vcc
	v_add_co_u32_e32 v50, vcc, 0x140000, v60
	s_nop 1
	v_addc_co_u32_e32 v51, vcc, 0, v61, vcc
	s_waitcnt vmcnt(4)
	v_add_co_u32_e32 v56, vcc, 0x180000, v60
	global_load_dwordx4 v[52:55], v[48:49], off nt
	s_nop 0
	global_load_dwordx4 v[48:51], v[50:51], off nt
	v_addc_co_u32_e32 v57, vcc, 0, v61, vcc
	global_load_dwordx4 v[56:59], v[56:57], off nt
	v_lshl_add_u64 v[60:61], v[60:61], 0, s[16:17]

; __device__ __forceinline__ void p0_item_load(const float* W, int N, int item, int lane, f32x4 (&wv)[8]) {
;     const int nblk = N / 32, kb = item / nblk, nb = item % nblk, k0 = 64 * kb, n0 = 32 * nb;
; #pragma unroll
;     for (int i = 0; i < 8; ++i) wv[i] = *(const f32x4*)(W + (size_t)(k0 + 8 * i + (lane >> 3)) * N + n0 + 4 * (lane & 7));
; }
; __device__ __forceinline__ void cv_load(const Args& a, int l, int it, int lane, f32x4 (&wv)[8]) {
;     ...
;     else if (it < CV_B) p0_item_load(a.in[I_WOUT] + (size_t)l * DM * DM, DM, it - CV_A, lane, wv);
;     else if (it < CV_C) p0_item_load(a.in[I_W1] + (size_t)l * DM * DFF, DFF, it - CV_B, lane, wv);
;     else p0_item_load(a.in[I_W2] + (size_t)l * DFF * DM, DM, it - CV_C, lane, wv);
; }
.LBB0_992:
	s_andn2_b64 vcc, exec, s[4:5]
	s_cbranch_vccnz .LBB0_994
	s_add_i32 s4, s10, 0xffffe9e0
	s_and_b32 s5, s4, 0xffc0
	s_waitcnt vmcnt(5)
	v_add_u32_e32 v32, s5, v80
	s_lshl_b32 s4, s4, 7
	s_and_b32 s84, s4, 0x1f80
	v_ashrrev_i32_e32 v33, 31, v32
	v_lshl_add_u64 v[34:35], v[68:69], 0, s[84:85]
	v_lshlrev_b64 v[32:33], 13, v[32:33]
	s_waitcnt vmcnt(0)
	v_lshl_add_u64 v[60:61], v[34:35], 0, v[32:33]
	v_add_co_u32_e32 v32, vcc, 0x10000, v60
	s_nop 1
	v_addc_co_u32_e32 v33, vcc, 0, v61, vcc
	s_waitcnt vmcnt(3)
	v_add_co_u32_e32 v40, vcc, 0x20000, v60
	global_load_dwordx4 v[36:39], v[60:61], off nt
	s_nop 0
	global_load_dwordx4 v[32:35], v[32:33], off nt
	v_addc_co_u32_e32 v41, vcc, 0, v61, vcc
	v_add_co_u32_e32 v42, vcc, 0x30000, v60
	s_nop 1
	v_addc_co_u32_e32 v43, vcc, 0, v61, vcc
	s_waitcnt vmcnt(3)
	v_add_co_u32_e32 v48, vcc, s90, v60
	global_load_dwordx4 v[44:47], v[40:41], off nt
	s_nop 0
	global_load_dwordx4 v[40:43], v[42:43], off nt
	v_addc_co_u32_e32 v49, vcc, 0, v61, vcc
	v_add_co_u32_e32 v50, vcc, 0x50000, v60
	s_nop 1
	v_addc_co_u32_e32 v51, vcc, 0, v61, vcc
	s_waitcnt vmcnt(4)
	v_add_co_u32_e32 v56, vcc, 0x60000, v60
	global_load_dwordx4 v[52:55], v[48:49], off nt
	s_nop 0
	global_load_dwordx4 v[48:51], v[50:51], off nt
	v_addc_co_u32_e32 v57, vcc, 0, v61, vcc
	global_load_dwordx4 v[56:59], v[56:57], off nt
	v_lshl_add_u64 v[60:61], v[60:61], 0, s[18:19]

; #define CV_MAP(g_, l_, it_) do { (l_) = lfix; \
;         if (MODE == 2) (it_) = CV_S0 + base + (g_); \
;         else if (MODE == 1) (it_) = cv_ritem(g_); \
;         else if ((g_) < CV_NR) (it_) = cv_ritem(g_); \
;         else { const int q_ = ((g_) - CV_NR) / CV_RPRO; (l_) = 1 + q_; (it_) = cv_ritem(CV_DEFER + ((g_) - CV_NR) - q_ * CV_RPRO); } } while (0)
; __device__ __forceinline__ void cv_load(const Args& a, int l, int it, int lane, f32x4 (&wv)[8]) {
;     ...
;     else if (it < CV_B) p0_item_load(a.in[I_WOUT] + (size_t)l * DM * DM, DM, it - CV_A, lane, wv);
;     else if (it < CV_C) p0_item_load(a.in[I_W1] + (size_t)l * DM * DFF, DFF, it - CV_B, lane, wv);
;     else p0_item_load(a.in[I_W2] + (size_t)l * DFF * DM, DM, it - CV_C, lane, wv);
; }
; template <int MODE>
; __device__ __forceinline__ void cv_jobs(const Frame& F, const Args& a, int lfix, int base, int njobs, int w, int nw) {
;     ...
;     for (int g = w; g < njobs; g += 2 * nw) {
;         const int g1 = g + nw; int l, it, l1, it1; CV_MAP(g, l, it); CV_MAP(g1, l1, it1);
;         cv_load(a, l, it, F.lane, sa);
;         if (g1 < njobs) cv_load(a, l1, it1, F.lane, sb);
;         cv_store(a, sa, scr, l, it, F.lane);
;         if (g1 < njobs) cv_store(a, sb, scr, l1, it1, F.lane);
;     }
.LBB0_995:
	s_andn2_b64 vcc, exec, s[4:5]
	s_mul_hi_i32 s13, s10, 0xb92143fb
	s_cbranch_vccnz .LBB0_997
	s_add_i32 s4, s13, s10
	s_lshr_b32 s5, s4, 31
	s_ashr_i32 s4, s4, 7
	s_add_i32 s5, s4, s5
	s_mul_i32 s4, s5, 0xb1
	s_sub_i32 s4, s10, s4
	s_lshl_b32 s4, s4, 5
	s_waitcnt vmcnt(0)
	v_lshl_add_u32 v62, s5, 6, v80
	s_ashr_i32 s5, s4, 31
	v_lshl_add_u64 v[60:61], s[4:5], 2, v[70:71]
	s_waitcnt vmcnt(5)
	v_add_u32_e32 v34, 8, v62
	s_waitcnt vmcnt(3)
	v_add_u32_e32 v40, 16, v62
	v_add_u32_e32 v42, 24, v62
	s_waitcnt vmcnt(1)
	v_add_u32_e32 v48, 32, v62
	v_add_u32_e32 v50, 40, v62
	s_waitcnt vmcnt(0)
	v_add_u32_e32 v56, 48, v62
	v_mad_i64_i32 v[32:33], s[4:5], v62, s14, v[60:61]
	v_mad_i64_i32 v[34:35], s[4:5], v34, s14, v[60:61]
	v_mad_i64_i32 v[40:41], s[4:5], v40, s14, v[60:61]
	v_mad_i64_i32 v[42:43], s[4:5], v42, s14, v[60:61]
	v_mad_i64_i32 v[48:49], s[4:5], v48, s14, v[60:61]
	v_mad_i64_i32 v[50:51], s[4:5], v50, s14, v[60:61]
	v_mad_i64_i32 v[56:57], s[4:5], v56, s14, v[60:61]
	global_load_dwordx4 v[36:39], v[32:33], off nt
	s_nop 0
	global_load_dwordx4 v[32:35], v[34:35], off nt
	s_nop 0
	global_load_dwordx4 v[44:47], v[40:41], off nt
	s_nop 0
	global_load_dwordx4 v[40:43], v[42:43], off nt
	s_nop 0
	global_load_dwordx4 v[52:55], v[48:49], off nt
	s_nop 0
	global_load_dwordx4 v[48:51], v[50:51], off nt
	v_add_u32_e32 v62, 56, v62
	global_load_dwordx4 v[56:59], v[56:57], off nt
	v_mad_i64_i32 v[60:61], s[4:5], v62, s14, v[60:61]
.LBB0_997:
	s_waitcnt vmcnt(0)
	global_load_dwordx4 v[60:63], v[60:61], off nt
	s_cmpk_lt_i32 s9, 0x1be0
	s_movk_i32 s4, 0x2240
	s_cselect_b32 s12, 0x400, s4
	s_add_i32 s12, s12, s8
	s_add_i32 s11, s12, 0x3e20
	s_cmpk_lt_i32 s9, 0x2c00
	s_cselect_b64 s[4:5], -1, 0
	s_cmpk_gt_i32 s9, 0x2bff
	s_cbranch_scc1 .LBB0_1013
	s_cmpk_gt_i32 s11, 0x161f
	s_mov_b64 s[6:7], -1
	s_cbranch_scc0 .LBB0_1008
	s_cmpk_gt_u32 s11, 0x1e1f
	s_cbranch_scc0 .LBB0_1005
	s_cmpk_gt_u32 s11, 0x3e1f
	s_cbranch_scc0 .LBB0_1002
	s_and_b32 s6, s12, 0xffffffc0
	v_add_u32_e32 v0, s6, v80
	s_lshl_b32 s6, s12, 7
	s_and_b32 s84, s6, 0x1f80
	v_ashrrev_i32_e32 v1, 31, v0
	v_lshl_add_u64 v[2:3], v[64:65], 0, s[84:85]
	v_lshlrev_b64 v[0:1], 13, v[0:1]
	v_lshl_add_u64 v[0:1], v[2:3], 0, v[0:1]
	s_mov_b64 s[6:7], 0x10000
	v_lshl_add_u64 v[4:5], v[0:1], 0, s[6:7]
	s_mov_b64 s[6:7], 0x20000
	v_lshl_add_u64 v[8:9], v[0:1], 0, s[6:7]
	s_mov_b64 s[6:7], 0x30000
	v_lshl_add_u64 v[12:13], v[0:1], 0, s[6:7]
	s_mov_b64 s[6:7], 0x50000
	v_lshl_add_u64 v[20:21], v[0:1], 0, s[6:7]
	s_mov_b64 s[6:7], 0x60000
	v_lshl_add_u64 v[16:17], v[0:1], 0, s[88:89]
	v_lshl_add_u64 v[24:25], v[0:1], 0, s[6:7]
	v_lshl_add_u64 v[28:29], v[0:1], 0, s[18:19]
	s_mov_b64 s[6:7], 0

; #define CV_MAP(g_, l_, it_) do { (l_) = lfix; \
;         if (MODE == 2) (it_) = CV_S0 + base + (g_); \
;         else if (MODE == 1) (it_) = cv_ritem(g_); \
;         else if ((g_) < CV_NR) (it_) = cv_ritem(g_); \
;         else { const int q_ = ((g_) - CV_NR) / CV_RPRO; (l_) = 1 + q_; (it_) = cv_ritem(CV_DEFER + ((g_) - CV_NR) - q_ * CV_RPRO); } } while (0)
; __device__ __forceinline__ void p0_item_load(const float* W, int N, int item, int lane, f32x4 (&wv)[8]) {
;     const int nblk = N / 32, kb = item / nblk, nb = item % nblk, k0 = 64 * kb, n0 = 32 * nb;
; #pragma unroll
;     for (int i = 0; i < 8; ++i) wv[i] = *(const f32x4*)(W + (size_t)(k0 + 8 * i + (lane >> 3)) * N + n0 + 4 * (lane & 7));
; }
; template <int MODE>
; __device__ __forceinline__ void cv_jobs(const Frame& F, const Args& a, int lfix, int base, int njobs, int w, int nw) {
;     ...
;         const int g1 = g + nw; int l, it, l1, it1; CV_MAP(g, l, it); CV_MAP(g1, l1, it1);
;         cv_load(a, l, it, F.lane, sa);
;         if (g1 < njobs) cv_load(a, l1, it1, F.lane, sb);
.LBB0_1010:
	global_load_dwordx4 v[0:3], v[0:1], off nt
	s_nop 0
	global_load_dwordx4 v[4:7], v[4:5], off nt
	s_nop 0
	global_load_dwordx4 v[8:11], v[8:9], off nt
	s_nop 0
	global_load_dwordx4 v[12:15], v[12:13], off nt
	s_nop 0
	global_load_dwordx4 v[16:19], v[16:17], off nt
	s_nop 0
	global_load_dwordx4 v[20:23], v[20:21], off nt
	s_nop 0
	global_load_dwordx4 v[24:27], v[24:25], off nt
	s_nop 0
	global_load_dwordx4 v[28:31], v[28:29], off nt
	s_mov_b64 s[6:7], -1
	s_and_b64 vcc, exec, s[2:3]
	s_cbranch_vccnz .LBB0_1014
